# pipelined LDS fragment reads also in the two position-DFT GEMM K-loops of the mixers phase, on top of v32
# speedup vs baseline: 1.0165x; 1.0028x over previous
.LBB0_612:
	s_add_i32 s5, s42, 2
	s_cmp_lt_u32 s42, 6
	s_cselect_b64 s[72:73], -1, 0
	s_and_b64 vcc, s[72:73], exec
	s_cselect_b32 s2, s39, 0x1c0
	s_lshl_b64 s[72:73], s[2:3], 1
	ds_read_b128 v[138:141], v134
	ds_read_b128 v[146:149], v135 offset:18432
	ds_read_b128 v[142:145], v134 offset:4608
	ds_read_b128 v[150:153], v135 offset:23040
	ds_read_b128 v[154:157], v134 offset:32
	ds_read_b128 v[162:165], v135 offset:18464
	ds_read_b128 v[158:161], v134 offset:4640
	ds_read_b128 v[166:169], v135 offset:23072
	v_lshl_add_u64 v[170:171], v[130:131], 0, s[72:73]
	v_lshl_add_u64 v[172:173], v[132:133], 0, s[72:73]
	global_load_dwordx4 v[98:101], v[170:171], off
	global_load_dwordx4 v[102:105], v[172:173], off
	v_lshl_add_u64 v[174:175], v[170:171], 0, s[78:79]
	global_load_dwordx4 v[106:109], v[174:175], off
	v_lshl_add_u64 v[174:175], v[172:173], 0, s[78:79]
	global_load_dwordx4 v[110:113], v[174:175], off
	v_lshl_add_u64 v[174:175], v[170:171], 0, s[40:41]
	global_load_dwordx4 v[114:117], v[174:175], off
	v_lshl_add_u64 v[174:175], v[172:173], 0, s[40:41]
	global_load_dwordx4 v[118:121], v[174:175], off
	v_lshl_add_u64 v[174:175], v[170:171], 0, s[56:57]
	global_load_dwordx4 v[122:125], v[174:175], off
	v_lshl_add_u64 v[174:175], v[172:173], 0, s[56:57]
	global_load_dwordx4 v[126:129], v[174:175], off
	s_waitcnt lgkmcnt(4)
	v_mfma_f32_32x32x16_bf16 v[48:63], v[138:141], v[146:149], v[48:63]
	v_mfma_f32_32x32x16_bf16 v[32:47], v[138:141], v[150:153], v[32:47]
	v_mfma_f32_32x32x16_bf16 v[16:31], v[142:145], v[146:149], v[16:31]
	v_mfma_f32_32x32x16_bf16 v[0:15], v[142:145], v[150:153], v[0:15]
	ds_read_b128 v[138:141], v134 offset:64
	ds_read_b128 v[146:149], v135 offset:18496
	ds_read_b128 v[142:145], v134 offset:4672
	ds_read_b128 v[150:153], v135 offset:23104
	s_waitcnt lgkmcnt(4)
	v_mfma_f32_32x32x16_bf16 v[48:63], v[154:157], v[162:165], v[48:63]
	v_mfma_f32_32x32x16_bf16 v[32:47], v[154:157], v[166:169], v[32:47]
	v_mfma_f32_32x32x16_bf16 v[16:31], v[158:161], v[162:165], v[16:31]
	v_mfma_f32_32x32x16_bf16 v[0:15], v[158:161], v[166:169], v[0:15]
	ds_read_b128 v[154:157], v134 offset:96
	ds_read_b128 v[162:165], v135 offset:18528
	ds_read_b128 v[158:161], v134 offset:4704
	ds_read_b128 v[166:169], v135 offset:23136
	s_waitcnt lgkmcnt(4)
	v_mfma_f32_32x32x16_bf16 v[48:63], v[138:141], v[146:149], v[48:63]
	s_waitcnt vmcnt(8)
	ds_write_b128 v97, v[64:67] offset:36864
	ds_write_b128 v97, v[68:71] offset:55296
	v_mfma_f32_32x32x16_bf16 v[32:47], v[138:141], v[150:153], v[32:47]
	ds_write_b128 v97, v[72:75] offset:41472
	ds_write_b128 v97, v[76:79] offset:59904
	v_mfma_f32_32x32x16_bf16 v[16:31], v[142:145], v[146:149], v[16:31]
	ds_write_b128 v97, v[80:83] offset:46080
	ds_write_b128 v97, v[84:87] offset:64512
	v_mfma_f32_32x32x16_bf16 v[0:15], v[142:145], v[150:153], v[0:15]
	ds_write_b128 v97, v[88:91] offset:50688
	ds_write_b128 v136, v[92:95] offset:55296
	s_waitcnt lgkmcnt(8)
	v_mfma_f32_32x32x16_bf16 v[48:63], v[154:157], v[162:165], v[48:63]
	v_mfma_f32_32x32x16_bf16 v[32:47], v[154:157], v[166:169], v[32:47]
	v_mfma_f32_32x32x16_bf16 v[16:31], v[158:161], v[162:165], v[16:31]
	v_mfma_f32_32x32x16_bf16 v[0:15], v[158:161], v[166:169], v[0:15]
	s_waitcnt lgkmcnt(0)
	s_barrier
	s_min_u32 s2, s42, 4
	s_lshl_b32 s2, s2, 7
	s_addk_i32 s39, 0x80
	s_mov_b32 s42, s5
	ds_read_b128 v[138:141], v134 offset:36864
	ds_read_b128 v[146:149], v135 offset:55296
	ds_read_b128 v[142:145], v134 offset:41472
	ds_read_b128 v[150:153], v135 offset:59904
	ds_read_b128 v[154:157], v134 offset:36896
	ds_read_b128 v[162:165], v135 offset:55328
	ds_read_b128 v[158:161], v134 offset:41504
	ds_read_b128 v[166:169], v135 offset:59936
	v_lshl_add_u64 v[170:171], v[130:131], 0, s[2:3]
	v_lshl_add_u64 v[172:173], v[132:133], 0, s[2:3]
	v_lshl_add_u64 v[174:175], v[170:171], 0, s[22:23]
	global_load_dwordx4 v[64:67], v[174:175], off
	v_lshl_add_u64 v[174:175], v[172:173], 0, s[22:23]
	global_load_dwordx4 v[68:71], v[174:175], off
	v_lshl_add_u64 v[174:175], v[170:171], 0, s[74:75]
	global_load_dwordx4 v[72:75], v[174:175], off
	v_lshl_add_u64 v[174:175], v[172:173], 0, s[74:75]
	global_load_dwordx4 v[76:79], v[174:175], off
	v_lshl_add_u64 v[174:175], v[170:171], 0, s[76:77]
	global_load_dwordx4 v[80:83], v[174:175], off
	v_lshl_add_u64 v[174:175], v[172:173], 0, s[76:77]
	global_load_dwordx4 v[84:87], v[174:175], off
	v_lshl_add_u64 v[174:175], v[170:171], 0, s[80:81]
	global_load_dwordx4 v[88:91], v[174:175], off
	v_lshl_add_u64 v[174:175], v[172:173], 0, s[80:81]
	global_load_dwordx4 v[92:95], v[174:175], off
	s_waitcnt lgkmcnt(4)
	v_mfma_f32_32x32x16_bf16 v[48:63], v[138:141], v[146:149], v[48:63]
	v_mfma_f32_32x32x16_bf16 v[32:47], v[138:141], v[150:153], v[32:47]
	v_mfma_f32_32x32x16_bf16 v[16:31], v[142:145], v[146:149], v[16:31]
	v_mfma_f32_32x32x16_bf16 v[0:15], v[142:145], v[150:153], v[0:15]
	ds_read_b128 v[138:141], v134 offset:36928
	ds_read_b128 v[146:149], v135 offset:55360
	ds_read_b128 v[142:145], v134 offset:41536
	ds_read_b128 v[150:153], v135 offset:59968
	s_waitcnt lgkmcnt(4)
	v_mfma_f32_32x32x16_bf16 v[48:63], v[154:157], v[162:165], v[48:63]
	v_mfma_f32_32x32x16_bf16 v[32:47], v[154:157], v[166:169], v[32:47]
	v_mfma_f32_32x32x16_bf16 v[16:31], v[158:161], v[162:165], v[16:31]
	v_mfma_f32_32x32x16_bf16 v[0:15], v[158:161], v[166:169], v[0:15]
	ds_read_b128 v[154:157], v134 offset:36960
	ds_read_b128 v[162:165], v135 offset:55392
	ds_read_b128 v[158:161], v134 offset:41568
	ds_read_b128 v[166:169], v135 offset:60000
	s_waitcnt lgkmcnt(4)
	v_mfma_f32_32x32x16_bf16 v[48:63], v[138:141], v[146:149], v[48:63]
	s_waitcnt vmcnt(8)
	ds_write_b128 v97, v[98:101]
	ds_write_b128 v97, v[102:105] offset:18432
	v_mfma_f32_32x32x16_bf16 v[32:47], v[138:141], v[150:153], v[32:47]
	ds_write_b128 v97, v[106:109] offset:4608
	ds_write_b128 v97, v[110:113] offset:23040
	v_mfma_f32_32x32x16_bf16 v[16:31], v[142:145], v[146:149], v[16:31]
	ds_write_b128 v97, v[114:117] offset:9216
	ds_write_b128 v97, v[118:121] offset:27648
	v_mfma_f32_32x32x16_bf16 v[0:15], v[142:145], v[150:153], v[0:15]
	ds_write_b128 v97, v[122:125] offset:13824
	ds_write_b128 v97, v[126:129] offset:32256
	s_waitcnt lgkmcnt(8)
	v_mfma_f32_32x32x16_bf16 v[48:63], v[154:157], v[162:165], v[48:63]
	v_mfma_f32_32x32x16_bf16 v[32:47], v[154:157], v[166:169], v[32:47]
	v_mfma_f32_32x32x16_bf16 v[16:31], v[158:161], v[162:165], v[16:31]
	v_mfma_f32_32x32x16_bf16 v[0:15], v[158:161], v[166:169], v[0:15]
	s_waitcnt lgkmcnt(0)
	s_barrier
	s_cbranch_vccnz .LBB0_612
	s_waitcnt vmcnt(0)
	s_lshl_b32 s2, s11, 4
	v_mov_b32_e32 v65, v244
	s_and_b32 s2, s2, 0x7fffff00
	s_lshl_b32 s5, s38, 7
	s_or_b32 s2, s2, s5
	v_lshrrev_b32_e32 v66, 3, v65
	v_and_or_b32 v66, v66, 4, s2
	s_lshl_b32 s2, s4, 9
	s_and_b32 s2, s2, 0x600
	v_ashrrev_i32_e32 v64, 1, v65
	s_add_u32 s2, s58, s2
	v_and_b32_e32 v64, 0xffffffc0, v64
	s_addc_u32 s5, s59, 0
	s_lshl_b32 s4, s10, 1
	v_add_u32_e32 v64, v66, v64
	v_and_b32_e32 v65, 0x5f, v65
	s_add_u32 s4, s2, s4
	s_addc_u32 s5, s5, 0
	v_lshlrev_b32_e32 v66, 1, v65
	v_mov_b32_e32 v67, v96
	v_ashrrev_i32_e32 v65, 31, v64
	v_lshl_add_u64 v[66:67], s[4:5], 0, v[66:67]
	v_mul_f32_e32 v48, 0x3b800000, v48
	v_lshlrev_b64 v[68:69], 11, v[64:65]
	v_cvt_pk_bf16_f32 v48, v48, v48
	v_lshl_add_u64 v[68:69], v[66:67], 0, v[68:69]
	global_store_short v[68:69], v48, off
	v_mul_f32_e32 v48, 0x3b800000, v49
	v_or_b32_e32 v70, 2, v64
	v_cvt_pk_bf16_f32 v65, v48, v48
	v_or_b32_e32 v48, 1, v64
	v_ashrrev_i32_e32 v71, 31, v70
	v_mul_f32_e32 v32, 0x3b800000, v32
	v_ashrrev_i32_e32 v49, 31, v48
	v_mul_f32_e32 v50, 0x3b800000, v50
	v_lshlrev_b64 v[70:71], 11, v[70:71]
	v_cvt_pk_bf16_f32 v32, v32, v32
	v_lshlrev_b64 v[48:49], 11, v[48:49]
	v_cvt_pk_bf16_f32 v50, v50, v50
	v_lshl_add_u64 v[70:71], v[66:67], 0, v[70:71]
	global_store_short v[68:69], v32, off offset:64
	v_mul_f32_e32 v32, 0x3b800000, v33
	v_lshl_add_u64 v[48:49], v[66:67], 0, v[48:49]
	global_store_short v[70:71], v50, off
	v_mul_f32_e32 v50, 0x3b800000, v51
	v_or_b32_e32 v72, 8, v64
	v_cvt_pk_bf16_f32 v32, v32, v32
	global_store_short v[48:49], v65, off
	v_cvt_pk_bf16_f32 v65, v50, v50
	v_or_b32_e32 v50, 3, v64
	v_ashrrev_i32_e32 v73, 31, v72
	global_store_short v[48:49], v32, off offset:64
	v_mul_f32_e32 v32, 0x3b800000, v34
	v_ashrrev_i32_e32 v51, 31, v50
	v_mul_f32_e32 v52, 0x3b800000, v52
	v_lshlrev_b64 v[72:73], 11, v[72:73]
	v_cvt_pk_bf16_f32 v32, v32, v32
	v_lshlrev_b64 v[50:51], 11, v[50:51]
	v_cvt_pk_bf16_f32 v52, v52, v52
	v_lshl_add_u64 v[72:73], v[66:67], 0, v[72:73]
	global_store_short v[70:71], v32, off offset:64
	v_mul_f32_e32 v32, 0x3b800000, v35
	v_lshl_add_u64 v[50:51], v[66:67], 0, v[50:51]
	global_store_short v[72:73], v52, off
	v_mul_f32_e32 v52, 0x3b800000, v53
	v_or_b32_e32 v74, 10, v64
	v_cvt_pk_bf16_f32 v32, v32, v32
	global_store_short v[50:51], v65, off
	v_cvt_pk_bf16_f32 v65, v52, v52
	v_or_b32_e32 v52, 9, v64
	v_ashrrev_i32_e32 v75, 31, v74
	global_store_short v[50:51], v32, off offset:64
	v_mul_f32_e32 v32, 0x3b800000, v36
	v_ashrrev_i32_e32 v53, 31, v52
	v_mul_f32_e32 v54, 0x3b800000, v54
	v_lshlrev_b64 v[74:75], 11, v[74:75]
	v_cvt_pk_bf16_f32 v32, v32, v32
	v_lshlrev_b64 v[52:53], 11, v[52:53]
	v_cvt_pk_bf16_f32 v54, v54, v54
	v_lshl_add_u64 v[74:75], v[66:67], 0, v[74:75]
	global_store_short v[72:73], v32, off offset:64
	v_mul_f32_e32 v32, 0x3b800000, v37
	v_lshl_add_u64 v[52:53], v[66:67], 0, v[52:53]
	global_store_short v[74:75], v54, off
	v_mul_f32_e32 v54, 0x3b800000, v55
	v_or_b32_e32 v76, 16, v64
	v_cvt_pk_bf16_f32 v32, v32, v32
	global_store_short v[52:53], v65, off
	v_cvt_pk_bf16_f32 v65, v54, v54
	v_or_b32_e32 v54, 11, v64
	v_ashrrev_i32_e32 v77, 31, v76
	global_store_short v[52:53], v32, off offset:64
	v_mul_f32_e32 v32, 0x3b800000, v38
	v_ashrrev_i32_e32 v55, 31, v54
	v_mul_f32_e32 v56, 0x3b800000, v56
	v_lshlrev_b64 v[76:77], 11, v[76:77]
	v_cvt_pk_bf16_f32 v32, v32, v32
	v_lshlrev_b64 v[54:55], 11, v[54:55]
	v_cvt_pk_bf16_f32 v56, v56, v56
	v_lshl_add_u64 v[76:77], v[66:67], 0, v[76:77]
	global_store_short v[74:75], v32, off offset:64
	v_mul_f32_e32 v32, 0x3b800000, v39
	v_lshl_add_u64 v[54:55], v[66:67], 0, v[54:55]
	global_store_short v[76:77], v56, off
	v_mul_f32_e32 v56, 0x3b800000, v57
	v_or_b32_e32 v78, 18, v64
	v_cvt_pk_bf16_f32 v32, v32, v32
	global_store_short v[54:55], v65, off
	v_cvt_pk_bf16_f32 v65, v56, v56
	v_or_b32_e32 v56, 17, v64
	v_ashrrev_i32_e32 v79, 31, v78
	global_store_short v[54:55], v32, off offset:64
	v_mul_f32_e32 v32, 0x3b800000, v40
	v_ashrrev_i32_e32 v57, 31, v56
	v_mul_f32_e32 v58, 0x3b800000, v58
	v_lshlrev_b64 v[78:79], 11, v[78:79]
	v_cvt_pk_bf16_f32 v32, v32, v32
	v_lshlrev_b64 v[56:57], 11, v[56:57]
	v_cvt_pk_bf16_f32 v58, v58, v58
	v_lshl_add_u64 v[78:79], v[66:67], 0, v[78:79]
	global_store_short v[76:77], v32, off offset:64
	v_mul_f32_e32 v32, 0x3b800000, v41
	v_lshl_add_u64 v[56:57], v[66:67], 0, v[56:57]
	global_store_short v[78:79], v58, off
	v_mul_f32_e32 v58, 0x3b800000, v59
	v_or_b32_e32 v80, 24, v64
	v_cvt_pk_bf16_f32 v32, v32, v32
	global_store_short v[56:57], v65, off
	v_cvt_pk_bf16_f32 v65, v58, v58
	v_or_b32_e32 v58, 19, v64
	v_ashrrev_i32_e32 v81, 31, v80
	global_store_short v[56:57], v32, off offset:64
	v_mul_f32_e32 v32, 0x3b800000, v42
	v_ashrrev_i32_e32 v59, 31, v58
	v_mul_f32_e32 v60, 0x3b800000, v60
	v_lshlrev_b64 v[80:81], 11, v[80:81]
	v_cvt_pk_bf16_f32 v32, v32, v32
	v_lshlrev_b64 v[58:59], 11, v[58:59]
	v_cvt_pk_bf16_f32 v60, v60, v60
	v_lshl_add_u64 v[80:81], v[66:67], 0, v[80:81]
	global_store_short v[78:79], v32, off offset:64
	v_mul_f32_e32 v32, 0x3b800000, v43
	v_lshl_add_u64 v[58:59], v[66:67], 0, v[58:59]
	global_store_short v[80:81], v60, off
	v_mul_f32_e32 v60, 0x3b800000, v61
	v_or_b32_e32 v82, 26, v64
	v_cvt_pk_bf16_f32 v32, v32, v32
	global_store_short v[58:59], v65, off
	v_cvt_pk_bf16_f32 v65, v60, v60
	v_or_b32_e32 v60, 25, v64
	v_ashrrev_i32_e32 v83, 31, v82
	global_store_short v[58:59], v32, off offset:64
	v_mul_f32_e32 v32, 0x3b800000, v44
	v_ashrrev_i32_e32 v61, 31, v60
	v_mul_f32_e32 v62, 0x3b800000, v62
	v_lshlrev_b64 v[82:83], 11, v[82:83]
	v_cvt_pk_bf16_f32 v32, v32, v32
	v_lshlrev_b64 v[60:61], 11, v[60:61]
	v_cvt_pk_bf16_f32 v62, v62, v62
	v_lshl_add_u64 v[82:83], v[66:67], 0, v[82:83]
	global_store_short v[80:81], v32, off offset:64
	v_mul_f32_e32 v32, 0x3b800000, v45
	v_lshl_add_u64 v[60:61], v[66:67], 0, v[60:61]
	global_store_short v[82:83], v62, off
	v_mul_f32_e32 v62, 0x3b800000, v63
	v_cvt_pk_bf16_f32 v32, v32, v32
	global_store_short v[60:61], v65, off
	v_cvt_pk_bf16_f32 v65, v62, v62
	v_or_b32_e32 v62, 27, v64
	global_store_short v[60:61], v32, off offset:64
	v_mul_f32_e32 v32, 0x3b800000, v46
	v_ashrrev_i32_e32 v63, 31, v62
	v_cvt_pk_bf16_f32 v32, v32, v32
	v_lshlrev_b64 v[62:63], 11, v[62:63]
	global_store_short v[82:83], v32, off offset:64
	v_mul_f32_e32 v32, 0x3b800000, v47
	v_lshl_add_u64 v[62:63], v[66:67], 0, v[62:63]
	v_cvt_pk_bf16_f32 v32, v32, v32
	global_store_short v[62:63], v32, off offset:64
	v_or_b32_e32 v32, 32, v64
	v_ashrrev_i32_e32 v33, 31, v32
	v_mul_f32_e32 v16, 0x3b800000, v16
	v_lshlrev_b64 v[32:33], 11, v[32:33]
	v_cvt_pk_bf16_f32 v16, v16, v16
	v_lshl_add_u64 v[32:33], v[66:67], 0, v[32:33]
	global_store_short v[32:33], v16, off
	v_mul_f32_e32 v16, 0x3b800000, v17
	v_cvt_pk_bf16_f32 v34, v16, v16
	v_or_b32_e32 v16, 33, v64
	v_ashrrev_i32_e32 v17, 31, v16
	v_lshlrev_b64 v[16:17], 11, v[16:17]
	v_lshl_add_u64 v[16:17], v[66:67], 0, v[16:17]
	global_store_short v[16:17], v34, off
	v_or_b32_e32 v34, 34, v64
	v_ashrrev_i32_e32 v35, 31, v34
	v_mul_f32_e32 v18, 0x3b800000, v18
	v_lshlrev_b64 v[34:35], 11, v[34:35]
	v_cvt_pk_bf16_f32 v18, v18, v18
	v_lshl_add_u64 v[34:35], v[66:67], 0, v[34:35]
	global_store_short v[34:35], v18, off
	v_mul_f32_e32 v18, 0x3b800000, v19
	v_cvt_pk_bf16_f32 v36, v18, v18
	v_or_b32_e32 v18, 35, v64
	v_ashrrev_i32_e32 v19, 31, v18
	v_lshlrev_b64 v[18:19], 11, v[18:19]
	v_lshl_add_u64 v[18:19], v[66:67], 0, v[18:19]
	global_store_short v[18:19], v36, off
	v_or_b32_e32 v36, 40, v64
	v_ashrrev_i32_e32 v37, 31, v36
	v_mul_f32_e32 v20, 0x3b800000, v20
	v_lshlrev_b64 v[36:37], 11, v[36:37]
	v_cvt_pk_bf16_f32 v20, v20, v20
	v_lshl_add_u64 v[36:37], v[66:67], 0, v[36:37]
	global_store_short v[36:37], v20, off
	v_mul_f32_e32 v20, 0x3b800000, v21
	v_cvt_pk_bf16_f32 v38, v20, v20
	v_or_b32_e32 v20, 41, v64
	v_ashrrev_i32_e32 v21, 31, v20
	v_lshlrev_b64 v[20:21], 11, v[20:21]
	v_lshl_add_u64 v[20:21], v[66:67], 0, v[20:21]
	global_store_short v[20:21], v38, off
	v_or_b32_e32 v38, 42, v64
	v_ashrrev_i32_e32 v39, 31, v38
	v_mul_f32_e32 v22, 0x3b800000, v22
	v_lshlrev_b64 v[38:39], 11, v[38:39]
	v_cvt_pk_bf16_f32 v22, v22, v22
	v_lshl_add_u64 v[38:39], v[66:67], 0, v[38:39]
	global_store_short v[38:39], v22, off
	v_mul_f32_e32 v22, 0x3b800000, v23
	v_cvt_pk_bf16_f32 v40, v22, v22
	v_or_b32_e32 v22, 43, v64
	v_ashrrev_i32_e32 v23, 31, v22
	v_lshlrev_b64 v[22:23], 11, v[22:23]
	v_lshl_add_u64 v[22:23], v[66:67], 0, v[22:23]
	global_store_short v[22:23], v40, off
	v_or_b32_e32 v40, 48, v64
	v_ashrrev_i32_e32 v41, 31, v40
	v_mul_f32_e32 v24, 0x3b800000, v24
	v_lshlrev_b64 v[40:41], 11, v[40:41]
	v_cvt_pk_bf16_f32 v24, v24, v24
	v_lshl_add_u64 v[40:41], v[66:67], 0, v[40:41]
	global_store_short v[40:41], v24, off
	v_mul_f32_e32 v24, 0x3b800000, v25
	v_cvt_pk_bf16_f32 v42, v24, v24
	v_or_b32_e32 v24, 49, v64
	v_mul_f32_e32 v0, 0x3b800000, v0
	v_ashrrev_i32_e32 v25, 31, v24
	v_cvt_pk_bf16_f32 v0, v0, v0
	v_lshlrev_b64 v[24:25], 11, v[24:25]
	global_store_short v[32:33], v0, off offset:64
	v_mul_f32_e32 v0, 0x3b800000, v1
	v_lshl_add_u64 v[24:25], v[66:67], 0, v[24:25]
	v_cvt_pk_bf16_f32 v0, v0, v0
	global_store_short v[24:25], v42, off
	v_or_b32_e32 v42, 50, v64
	global_store_short v[16:17], v0, off offset:64
	v_mul_f32_e32 v0, 0x3b800000, v2
	v_ashrrev_i32_e32 v43, 31, v42
	v_cvt_pk_bf16_f32 v0, v0, v0
	v_mul_f32_e32 v26, 0x3b800000, v26
	v_lshlrev_b64 v[42:43], 11, v[42:43]
	global_store_short v[34:35], v0, off offset:64
	v_mul_f32_e32 v0, 0x3b800000, v3
	v_cvt_pk_bf16_f32 v26, v26, v26
	v_lshl_add_u64 v[42:43], v[66:67], 0, v[42:43]
	v_cvt_pk_bf16_f32 v0, v0, v0
	global_store_short v[42:43], v26, off
	v_mul_f32_e32 v26, 0x3b800000, v27
	global_store_short v[18:19], v0, off offset:64
	v_mul_f32_e32 v0, 0x3b800000, v4
	v_cvt_pk_bf16_f32 v44, v26, v26
	v_or_b32_e32 v26, 51, v64
	v_cvt_pk_bf16_f32 v0, v0, v0
	v_ashrrev_i32_e32 v27, 31, v26
	global_store_short v[36:37], v0, off offset:64
	v_mul_f32_e32 v0, 0x3b800000, v5
	v_lshlrev_b64 v[26:27], 11, v[26:27]
	v_cvt_pk_bf16_f32 v0, v0, v0
	v_lshl_add_u64 v[26:27], v[66:67], 0, v[26:27]
	global_store_short v[20:21], v0, off offset:64
	v_mul_f32_e32 v0, 0x3b800000, v6
	global_store_short v[26:27], v44, off
	v_or_b32_e32 v44, 56, v64
	v_cvt_pk_bf16_f32 v0, v0, v0
	v_ashrrev_i32_e32 v45, 31, v44
	global_store_short v[38:39], v0, off offset:64
	v_mul_f32_e32 v0, 0x3b800000, v7
	v_mul_f32_e32 v28, 0x3b800000, v28
	v_lshlrev_b64 v[44:45], 11, v[44:45]
	v_cvt_pk_bf16_f32 v0, v0, v0
	v_cvt_pk_bf16_f32 v28, v28, v28
	v_lshl_add_u64 v[44:45], v[66:67], 0, v[44:45]
	global_store_short v[22:23], v0, off offset:64
	v_mul_f32_e32 v0, 0x3b800000, v8
	global_store_short v[44:45], v28, off
	v_mul_f32_e32 v28, 0x3b800000, v29
	v_cvt_pk_bf16_f32 v0, v0, v0
	v_cvt_pk_bf16_f32 v46, v28, v28
	v_or_b32_e32 v28, 57, v64
	global_store_short v[40:41], v0, off offset:64
	v_mul_f32_e32 v0, 0x3b800000, v9
	v_ashrrev_i32_e32 v29, 31, v28
	v_cvt_pk_bf16_f32 v0, v0, v0
	v_lshlrev_b64 v[28:29], 11, v[28:29]
	global_store_short v[24:25], v0, off offset:64
	v_mul_f32_e32 v0, 0x3b800000, v10
	v_lshl_add_u64 v[28:29], v[66:67], 0, v[28:29]
	v_cvt_pk_bf16_f32 v0, v0, v0
	global_store_short v[28:29], v46, off
	v_or_b32_e32 v46, 58, v64
	global_store_short v[42:43], v0, off offset:64
	v_mul_f32_e32 v0, 0x3b800000, v11
	v_ashrrev_i32_e32 v47, 31, v46
	v_cvt_pk_bf16_f32 v0, v0, v0
	v_mul_f32_e32 v30, 0x3b800000, v30
	v_lshlrev_b64 v[46:47], 11, v[46:47]
	global_store_short v[26:27], v0, off offset:64
	v_mul_f32_e32 v0, 0x3b800000, v12
	v_cvt_pk_bf16_f32 v30, v30, v30
	v_lshl_add_u64 v[46:47], v[66:67], 0, v[46:47]
	v_cvt_pk_bf16_f32 v0, v0, v0
	global_store_short v[46:47], v30, off
	v_mul_f32_e32 v30, 0x3b800000, v31
	global_store_short v[44:45], v0, off offset:64
	v_mul_f32_e32 v0, 0x3b800000, v13
	v_cvt_pk_bf16_f32 v48, v30, v30
	v_or_b32_e32 v30, 59, v64
	v_cvt_pk_bf16_f32 v0, v0, v0
	v_ashrrev_i32_e32 v31, 31, v30
	global_store_short v[28:29], v0, off offset:64
	v_mul_f32_e32 v0, 0x3b800000, v14
	v_lshlrev_b64 v[30:31], 11, v[30:31]
	v_cvt_pk_bf16_f32 v0, v0, v0
	s_mov_b64 s[88:89], 0x18000
	v_lshl_add_u64 v[30:31], v[66:67], 0, v[30:31]
	global_store_short v[46:47], v0, off offset:64
	v_mul_f32_e32 v0, 0x3b800000, v15
	global_store_short v[62:63], v65, off
	global_store_short v[30:31], v48, off
	v_cvt_pk_bf16_f32 v0, v0, v0
	global_store_short v[30:31], v0, off offset:64

.LBB0_617:
	s_add_i32 s5, s42, 2
	s_cmp_lt_u32 s42, 30
	s_cselect_b64 s[72:73], -1, 0
	s_and_b64 vcc, s[72:73], exec
	s_cselect_b32 s2, s39, 0x7c0
	s_lshl_b64 s[72:73], s[2:3], 1
	ds_read_b128 v[138:141], v134
	ds_read_b128 v[146:149], v135 offset:18432
	ds_read_b128 v[142:145], v134 offset:4608
	ds_read_b128 v[150:153], v135 offset:23040
	ds_read_b128 v[154:157], v134 offset:32
	ds_read_b128 v[162:165], v135 offset:18464
	ds_read_b128 v[158:161], v134 offset:4640
	ds_read_b128 v[166:169], v135 offset:23072
	v_lshl_add_u64 v[170:171], v[130:131], 0, s[72:73]
	v_lshl_add_u64 v[172:173], v[132:133], 0, s[72:73]
	global_load_dwordx4 v[98:101], v[170:171], off
	global_load_dwordx4 v[102:105], v[172:173], off
	v_lshl_add_u64 v[174:175], v[170:171], 0, s[18:19]
	global_load_dwordx4 v[106:109], v[174:175], off
	v_lshl_add_u64 v[174:175], v[172:173], 0, s[18:19]
	global_load_dwordx4 v[110:113], v[174:175], off
	v_lshl_add_u64 v[174:175], v[170:171], 0, s[56:57]
	global_load_dwordx4 v[114:117], v[174:175], off
	v_lshl_add_u64 v[174:175], v[172:173], 0, s[56:57]
	global_load_dwordx4 v[118:121], v[174:175], off
	v_lshl_add_u64 v[174:175], v[170:171], 0, s[74:75]
	global_load_dwordx4 v[122:125], v[174:175], off
	v_lshl_add_u64 v[174:175], v[172:173], 0, s[74:75]
	global_load_dwordx4 v[126:129], v[174:175], off
	s_waitcnt lgkmcnt(4)
	v_mfma_f32_32x32x16_bf16 v[48:63], v[138:141], v[146:149], v[48:63]
	v_mfma_f32_32x32x16_bf16 v[32:47], v[138:141], v[150:153], v[32:47]
	v_mfma_f32_32x32x16_bf16 v[16:31], v[142:145], v[146:149], v[16:31]
	v_mfma_f32_32x32x16_bf16 v[0:15], v[142:145], v[150:153], v[0:15]
	ds_read_b128 v[138:141], v134 offset:64
	ds_read_b128 v[146:149], v135 offset:18496
	ds_read_b128 v[142:145], v134 offset:4672
	ds_read_b128 v[150:153], v135 offset:23104
	s_waitcnt lgkmcnt(4)
	v_mfma_f32_32x32x16_bf16 v[48:63], v[154:157], v[162:165], v[48:63]
	v_mfma_f32_32x32x16_bf16 v[32:47], v[154:157], v[166:169], v[32:47]
	v_mfma_f32_32x32x16_bf16 v[16:31], v[158:161], v[162:165], v[16:31]
	v_mfma_f32_32x32x16_bf16 v[0:15], v[158:161], v[166:169], v[0:15]
	ds_read_b128 v[154:157], v134 offset:96
	ds_read_b128 v[162:165], v135 offset:18528
	ds_read_b128 v[158:161], v134 offset:4704
	ds_read_b128 v[166:169], v135 offset:23136
	s_waitcnt lgkmcnt(4)
	v_mfma_f32_32x32x16_bf16 v[48:63], v[138:141], v[146:149], v[48:63]
	s_waitcnt vmcnt(8)
	ds_write_b128 v97, v[64:67] offset:36864
	ds_write_b128 v97, v[68:71] offset:55296
	v_mfma_f32_32x32x16_bf16 v[32:47], v[138:141], v[150:153], v[32:47]
	ds_write_b128 v97, v[72:75] offset:41472
	ds_write_b128 v97, v[76:79] offset:59904
	v_mfma_f32_32x32x16_bf16 v[16:31], v[142:145], v[146:149], v[16:31]
	ds_write_b128 v97, v[80:83] offset:46080
	ds_write_b128 v97, v[84:87] offset:64512
	v_mfma_f32_32x32x16_bf16 v[0:15], v[142:145], v[150:153], v[0:15]
	ds_write_b128 v97, v[88:91] offset:50688
	ds_write_b128 v136, v[92:95] offset:55296
	s_waitcnt lgkmcnt(8)
	v_mfma_f32_32x32x16_bf16 v[48:63], v[154:157], v[162:165], v[48:63]
	v_mfma_f32_32x32x16_bf16 v[32:47], v[154:157], v[166:169], v[32:47]
	v_mfma_f32_32x32x16_bf16 v[16:31], v[158:161], v[162:165], v[16:31]
	v_mfma_f32_32x32x16_bf16 v[0:15], v[158:161], v[166:169], v[0:15]
	s_waitcnt lgkmcnt(0)
	s_barrier
	s_min_u32 s2, s42, 28
	s_lshl_b32 s2, s2, 7
	s_addk_i32 s39, 0x80
	s_mov_b32 s42, s5
	ds_read_b128 v[138:141], v134 offset:36864
	ds_read_b128 v[146:149], v135 offset:55296
	ds_read_b128 v[142:145], v134 offset:41472
	ds_read_b128 v[150:153], v135 offset:59904
	ds_read_b128 v[154:157], v134 offset:36896
	ds_read_b128 v[162:165], v135 offset:55328
	ds_read_b128 v[158:161], v134 offset:41504
	ds_read_b128 v[166:169], v135 offset:59936
	v_lshl_add_u64 v[170:171], v[130:131], 0, s[2:3]
	v_lshl_add_u64 v[172:173], v[132:133], 0, s[2:3]
	v_lshl_add_u64 v[174:175], v[170:171], 0, s[22:23]
	global_load_dwordx4 v[64:67], v[174:175], off
	v_lshl_add_u64 v[174:175], v[172:173], 0, s[22:23]
	global_load_dwordx4 v[68:71], v[174:175], off
	v_lshl_add_u64 v[174:175], v[170:171], 0, s[26:27]
	global_load_dwordx4 v[72:75], v[174:175], off
	v_lshl_add_u64 v[174:175], v[172:173], 0, s[26:27]
	global_load_dwordx4 v[76:79], v[174:175], off
	v_lshl_add_u64 v[174:175], v[170:171], 0, s[76:77]
	global_load_dwordx4 v[80:83], v[174:175], off
	v_lshl_add_u64 v[174:175], v[172:173], 0, s[76:77]
	global_load_dwordx4 v[84:87], v[174:175], off
	v_lshl_add_u64 v[174:175], v[170:171], 0, s[78:79]
	global_load_dwordx4 v[88:91], v[174:175], off
	v_lshl_add_u64 v[174:175], v[172:173], 0, s[78:79]
	global_load_dwordx4 v[92:95], v[174:175], off
	s_waitcnt lgkmcnt(4)
	v_mfma_f32_32x32x16_bf16 v[48:63], v[138:141], v[146:149], v[48:63]
	v_mfma_f32_32x32x16_bf16 v[32:47], v[138:141], v[150:153], v[32:47]
	v_mfma_f32_32x32x16_bf16 v[16:31], v[142:145], v[146:149], v[16:31]
	v_mfma_f32_32x32x16_bf16 v[0:15], v[142:145], v[150:153], v[0:15]
	ds_read_b128 v[138:141], v134 offset:36928
	ds_read_b128 v[146:149], v135 offset:55360
	ds_read_b128 v[142:145], v134 offset:41536
	ds_read_b128 v[150:153], v135 offset:59968
	s_waitcnt lgkmcnt(4)
	v_mfma_f32_32x32x16_bf16 v[48:63], v[154:157], v[162:165], v[48:63]
	v_mfma_f32_32x32x16_bf16 v[32:47], v[154:157], v[166:169], v[32:47]
	v_mfma_f32_32x32x16_bf16 v[16:31], v[158:161], v[162:165], v[16:31]
	v_mfma_f32_32x32x16_bf16 v[0:15], v[158:161], v[166:169], v[0:15]
	ds_read_b128 v[154:157], v134 offset:36960
	ds_read_b128 v[162:165], v135 offset:55392
	ds_read_b128 v[158:161], v134 offset:41568
	ds_read_b128 v[166:169], v135 offset:60000
	s_waitcnt lgkmcnt(4)
	v_mfma_f32_32x32x16_bf16 v[48:63], v[138:141], v[146:149], v[48:63]
	s_waitcnt vmcnt(8)
	ds_write_b128 v97, v[98:101]
	ds_write_b128 v97, v[102:105] offset:18432
	v_mfma_f32_32x32x16_bf16 v[32:47], v[138:141], v[150:153], v[32:47]
	ds_write_b128 v97, v[106:109] offset:4608
	ds_write_b128 v97, v[110:113] offset:23040
	v_mfma_f32_32x32x16_bf16 v[16:31], v[142:145], v[146:149], v[16:31]
	ds_write_b128 v97, v[114:117] offset:9216
	ds_write_b128 v97, v[118:121] offset:27648
	v_mfma_f32_32x32x16_bf16 v[0:15], v[142:145], v[150:153], v[0:15]
	ds_write_b128 v97, v[122:125] offset:13824
	ds_write_b128 v97, v[126:129] offset:32256
	s_waitcnt lgkmcnt(8)
	v_mfma_f32_32x32x16_bf16 v[48:63], v[154:157], v[162:165], v[48:63]
	v_mfma_f32_32x32x16_bf16 v[32:47], v[154:157], v[166:169], v[32:47]
	v_mfma_f32_32x32x16_bf16 v[16:31], v[158:161], v[162:165], v[16:31]
	v_mfma_f32_32x32x16_bf16 v[0:15], v[158:161], v[166:169], v[0:15]
	s_waitcnt lgkmcnt(0)
	s_barrier
	s_cbranch_vccnz .LBB0_617
	s_lshl_b32 s2, s11, 4
	s_waitcnt vmcnt(0)
	s_and_b32 s2, s2, 0x7ffffc00
	s_lshl_b32 s5, s38, 7
	v_mov_b32_e32 v65, v244
	s_or_b32 s2, s2, s5
	s_addk_i32 s2, 0x1000
	v_lshrrev_b32_e32 v66, 3, v65
	v_and_or_b32 v66, v66, 4, s2
	s_lshl_b32 s2, s4, 9
	s_and_b32 s2, s2, 0x600
	v_ashrrev_i32_e32 v64, 1, v65
	s_add_u32 s2, s58, s2
	v_and_b32_e32 v64, 0xffffffc0, v64
	s_addc_u32 s5, s59, 0
	s_lshl_b32 s4, s10, 1
	v_add_u32_e32 v64, v66, v64
	v_and_b32_e32 v65, 0x5f, v65
	s_add_u32 s4, s2, s4
	s_addc_u32 s5, s5, 0
	v_lshlrev_b32_e32 v66, 1, v65
	v_mov_b32_e32 v67, v96
	v_ashrrev_i32_e32 v65, 31, v64
	v_lshl_add_u64 v[66:67], s[4:5], 0, v[66:67]
	v_mul_f32_e32 v48, 0x3b000000, v48
	v_lshlrev_b64 v[68:69], 11, v[64:65]
	v_cvt_pk_bf16_f32 v48, v48, v48
	v_lshl_add_u64 v[68:69], v[66:67], 0, v[68:69]
	global_store_short v[68:69], v48, off
	v_mul_f32_e32 v48, 0x3b000000, v49
	v_or_b32_e32 v70, 2, v64
	v_cvt_pk_bf16_f32 v65, v48, v48
	v_or_b32_e32 v48, 1, v64
	v_ashrrev_i32_e32 v71, 31, v70
	v_mul_f32_e32 v32, 0x3b000000, v32
	v_ashrrev_i32_e32 v49, 31, v48
	v_mul_f32_e32 v50, 0x3b000000, v50
	v_lshlrev_b64 v[70:71], 11, v[70:71]
	v_cvt_pk_bf16_f32 v32, v32, v32
	v_lshlrev_b64 v[48:49], 11, v[48:49]
	v_cvt_pk_bf16_f32 v50, v50, v50
	v_lshl_add_u64 v[70:71], v[66:67], 0, v[70:71]
	global_store_short v[68:69], v32, off offset:64
	v_mul_f32_e32 v32, 0x3b000000, v33
	v_lshl_add_u64 v[48:49], v[66:67], 0, v[48:49]
	global_store_short v[70:71], v50, off
	v_mul_f32_e32 v50, 0x3b000000, v51
	v_or_b32_e32 v72, 8, v64
	v_cvt_pk_bf16_f32 v32, v32, v32
	global_store_short v[48:49], v65, off
	v_cvt_pk_bf16_f32 v65, v50, v50
	v_or_b32_e32 v50, 3, v64
	v_ashrrev_i32_e32 v73, 31, v72
	global_store_short v[48:49], v32, off offset:64
	v_mul_f32_e32 v32, 0x3b000000, v34
	v_ashrrev_i32_e32 v51, 31, v50
	v_mul_f32_e32 v52, 0x3b000000, v52
	v_lshlrev_b64 v[72:73], 11, v[72:73]
	v_cvt_pk_bf16_f32 v32, v32, v32
	v_lshlrev_b64 v[50:51], 11, v[50:51]
	v_cvt_pk_bf16_f32 v52, v52, v52
	v_lshl_add_u64 v[72:73], v[66:67], 0, v[72:73]
	global_store_short v[70:71], v32, off offset:64
	v_mul_f32_e32 v32, 0x3b000000, v35
	v_lshl_add_u64 v[50:51], v[66:67], 0, v[50:51]
	global_store_short v[72:73], v52, off
	v_mul_f32_e32 v52, 0x3b000000, v53
	v_or_b32_e32 v74, 10, v64
	v_cvt_pk_bf16_f32 v32, v32, v32
	global_store_short v[50:51], v65, off
	v_cvt_pk_bf16_f32 v65, v52, v52
	v_or_b32_e32 v52, 9, v64
	v_ashrrev_i32_e32 v75, 31, v74
	global_store_short v[50:51], v32, off offset:64
	v_mul_f32_e32 v32, 0x3b000000, v36
	v_ashrrev_i32_e32 v53, 31, v52
	v_mul_f32_e32 v54, 0x3b000000, v54
	v_lshlrev_b64 v[74:75], 11, v[74:75]
	v_cvt_pk_bf16_f32 v32, v32, v32
	v_lshlrev_b64 v[52:53], 11, v[52:53]
	v_cvt_pk_bf16_f32 v54, v54, v54
	v_lshl_add_u64 v[74:75], v[66:67], 0, v[74:75]
	global_store_short v[72:73], v32, off offset:64
	v_mul_f32_e32 v32, 0x3b000000, v37
	v_lshl_add_u64 v[52:53], v[66:67], 0, v[52:53]
	global_store_short v[74:75], v54, off
	v_mul_f32_e32 v54, 0x3b000000, v55
	v_or_b32_e32 v76, 16, v64
	v_cvt_pk_bf16_f32 v32, v32, v32
	global_store_short v[52:53], v65, off
	v_cvt_pk_bf16_f32 v65, v54, v54
	v_or_b32_e32 v54, 11, v64
	v_ashrrev_i32_e32 v77, 31, v76
	global_store_short v[52:53], v32, off offset:64
	v_mul_f32_e32 v32, 0x3b000000, v38
	v_ashrrev_i32_e32 v55, 31, v54
	v_mul_f32_e32 v56, 0x3b000000, v56
	v_lshlrev_b64 v[76:77], 11, v[76:77]
	v_cvt_pk_bf16_f32 v32, v32, v32
	v_lshlrev_b64 v[54:55], 11, v[54:55]
	v_cvt_pk_bf16_f32 v56, v56, v56
	v_lshl_add_u64 v[76:77], v[66:67], 0, v[76:77]
	global_store_short v[74:75], v32, off offset:64
	v_mul_f32_e32 v32, 0x3b000000, v39
	v_lshl_add_u64 v[54:55], v[66:67], 0, v[54:55]
	global_store_short v[76:77], v56, off
	v_mul_f32_e32 v56, 0x3b000000, v57
	v_or_b32_e32 v78, 18, v64
	v_cvt_pk_bf16_f32 v32, v32, v32
	global_store_short v[54:55], v65, off
	v_cvt_pk_bf16_f32 v65, v56, v56
	v_or_b32_e32 v56, 17, v64
	v_ashrrev_i32_e32 v79, 31, v78
	global_store_short v[54:55], v32, off offset:64
	v_mul_f32_e32 v32, 0x3b000000, v40
	v_ashrrev_i32_e32 v57, 31, v56
	v_mul_f32_e32 v58, 0x3b000000, v58
	v_lshlrev_b64 v[78:79], 11, v[78:79]
	v_cvt_pk_bf16_f32 v32, v32, v32
	v_lshlrev_b64 v[56:57], 11, v[56:57]
	v_cvt_pk_bf16_f32 v58, v58, v58
	v_lshl_add_u64 v[78:79], v[66:67], 0, v[78:79]
	global_store_short v[76:77], v32, off offset:64
	v_mul_f32_e32 v32, 0x3b000000, v41
	v_lshl_add_u64 v[56:57], v[66:67], 0, v[56:57]
	global_store_short v[78:79], v58, off
	v_mul_f32_e32 v58, 0x3b000000, v59
	v_or_b32_e32 v80, 24, v64
	v_cvt_pk_bf16_f32 v32, v32, v32
	global_store_short v[56:57], v65, off
	v_cvt_pk_bf16_f32 v65, v58, v58
	v_or_b32_e32 v58, 19, v64
	v_ashrrev_i32_e32 v81, 31, v80
	global_store_short v[56:57], v32, off offset:64
	v_mul_f32_e32 v32, 0x3b000000, v42
	v_ashrrev_i32_e32 v59, 31, v58
	v_mul_f32_e32 v60, 0x3b000000, v60
	v_lshlrev_b64 v[80:81], 11, v[80:81]
	v_cvt_pk_bf16_f32 v32, v32, v32
	v_lshlrev_b64 v[58:59], 11, v[58:59]
	v_cvt_pk_bf16_f32 v60, v60, v60
	v_lshl_add_u64 v[80:81], v[66:67], 0, v[80:81]
	global_store_short v[78:79], v32, off offset:64
	v_mul_f32_e32 v32, 0x3b000000, v43
	v_lshl_add_u64 v[58:59], v[66:67], 0, v[58:59]
	global_store_short v[80:81], v60, off
	v_mul_f32_e32 v60, 0x3b000000, v61
	v_or_b32_e32 v82, 26, v64
	v_cvt_pk_bf16_f32 v32, v32, v32
	global_store_short v[58:59], v65, off
	v_cvt_pk_bf16_f32 v65, v60, v60
	v_or_b32_e32 v60, 25, v64
	v_ashrrev_i32_e32 v83, 31, v82
	global_store_short v[58:59], v32, off offset:64
	v_mul_f32_e32 v32, 0x3b000000, v44
	v_ashrrev_i32_e32 v61, 31, v60
	v_mul_f32_e32 v62, 0x3b000000, v62
	v_lshlrev_b64 v[82:83], 11, v[82:83]
	v_cvt_pk_bf16_f32 v32, v32, v32
	v_lshlrev_b64 v[60:61], 11, v[60:61]
	v_cvt_pk_bf16_f32 v62, v62, v62
	v_lshl_add_u64 v[82:83], v[66:67], 0, v[82:83]
	global_store_short v[80:81], v32, off offset:64
	v_mul_f32_e32 v32, 0x3b000000, v45
	v_lshl_add_u64 v[60:61], v[66:67], 0, v[60:61]
	global_store_short v[82:83], v62, off
	v_mul_f32_e32 v62, 0x3b000000, v63
	v_cvt_pk_bf16_f32 v32, v32, v32
	global_store_short v[60:61], v65, off
	v_cvt_pk_bf16_f32 v65, v62, v62
	v_or_b32_e32 v62, 27, v64
	global_store_short v[60:61], v32, off offset:64
	v_mul_f32_e32 v32, 0x3b000000, v46
	v_ashrrev_i32_e32 v63, 31, v62
	v_cvt_pk_bf16_f32 v32, v32, v32
	v_lshlrev_b64 v[62:63], 11, v[62:63]
	global_store_short v[82:83], v32, off offset:64
	v_mul_f32_e32 v32, 0x3b000000, v47
	v_lshl_add_u64 v[62:63], v[66:67], 0, v[62:63]
	v_cvt_pk_bf16_f32 v32, v32, v32
	global_store_short v[62:63], v32, off offset:64
	v_or_b32_e32 v32, 32, v64
	v_ashrrev_i32_e32 v33, 31, v32
	v_mul_f32_e32 v16, 0x3b000000, v16
	v_lshlrev_b64 v[32:33], 11, v[32:33]
	v_cvt_pk_bf16_f32 v16, v16, v16
	v_lshl_add_u64 v[32:33], v[66:67], 0, v[32:33]
	global_store_short v[32:33], v16, off
	v_mul_f32_e32 v16, 0x3b000000, v17
	v_cvt_pk_bf16_f32 v34, v16, v16
	v_or_b32_e32 v16, 33, v64
	v_ashrrev_i32_e32 v17, 31, v16
	v_lshlrev_b64 v[16:17], 11, v[16:17]
	v_lshl_add_u64 v[16:17], v[66:67], 0, v[16:17]
	global_store_short v[16:17], v34, off
	v_or_b32_e32 v34, 34, v64
	v_ashrrev_i32_e32 v35, 31, v34
	v_mul_f32_e32 v18, 0x3b000000, v18
	v_lshlrev_b64 v[34:35], 11, v[34:35]
	v_cvt_pk_bf16_f32 v18, v18, v18
	v_lshl_add_u64 v[34:35], v[66:67], 0, v[34:35]
	global_store_short v[34:35], v18, off
	v_mul_f32_e32 v18, 0x3b000000, v19
	v_cvt_pk_bf16_f32 v36, v18, v18
	v_or_b32_e32 v18, 35, v64
	v_ashrrev_i32_e32 v19, 31, v18
	v_lshlrev_b64 v[18:19], 11, v[18:19]
	v_lshl_add_u64 v[18:19], v[66:67], 0, v[18:19]
	global_store_short v[18:19], v36, off
	v_or_b32_e32 v36, 40, v64
	v_ashrrev_i32_e32 v37, 31, v36
	v_mul_f32_e32 v20, 0x3b000000, v20
	v_lshlrev_b64 v[36:37], 11, v[36:37]
	v_cvt_pk_bf16_f32 v20, v20, v20
	v_lshl_add_u64 v[36:37], v[66:67], 0, v[36:37]
	global_store_short v[36:37], v20, off
	v_mul_f32_e32 v20, 0x3b000000, v21
	v_cvt_pk_bf16_f32 v38, v20, v20
	v_or_b32_e32 v20, 41, v64
	v_ashrrev_i32_e32 v21, 31, v20
	v_lshlrev_b64 v[20:21], 11, v[20:21]
	v_lshl_add_u64 v[20:21], v[66:67], 0, v[20:21]
	global_store_short v[20:21], v38, off
	v_or_b32_e32 v38, 42, v64
	v_ashrrev_i32_e32 v39, 31, v38
	v_mul_f32_e32 v22, 0x3b000000, v22
	v_lshlrev_b64 v[38:39], 11, v[38:39]
	v_cvt_pk_bf16_f32 v22, v22, v22
	v_lshl_add_u64 v[38:39], v[66:67], 0, v[38:39]
	global_store_short v[38:39], v22, off
	v_mul_f32_e32 v22, 0x3b000000, v23
	v_cvt_pk_bf16_f32 v40, v22, v22
	v_or_b32_e32 v22, 43, v64
	v_ashrrev_i32_e32 v23, 31, v22
	v_lshlrev_b64 v[22:23], 11, v[22:23]
	v_lshl_add_u64 v[22:23], v[66:67], 0, v[22:23]
	global_store_short v[22:23], v40, off
	v_or_b32_e32 v40, 48, v64
	v_ashrrev_i32_e32 v41, 31, v40
	v_mul_f32_e32 v24, 0x3b000000, v24
	v_lshlrev_b64 v[40:41], 11, v[40:41]
	v_cvt_pk_bf16_f32 v24, v24, v24
	v_lshl_add_u64 v[40:41], v[66:67], 0, v[40:41]
	global_store_short v[40:41], v24, off
	v_mul_f32_e32 v24, 0x3b000000, v25
	v_cvt_pk_bf16_f32 v42, v24, v24
	v_or_b32_e32 v24, 49, v64
	v_mul_f32_e32 v0, 0x3b000000, v0
	v_ashrrev_i32_e32 v25, 31, v24
	v_cvt_pk_bf16_f32 v0, v0, v0
	v_lshlrev_b64 v[24:25], 11, v[24:25]
	global_store_short v[32:33], v0, off offset:64
	v_mul_f32_e32 v0, 0x3b000000, v1
	v_lshl_add_u64 v[24:25], v[66:67], 0, v[24:25]
	v_cvt_pk_bf16_f32 v0, v0, v0
	global_store_short v[24:25], v42, off
	v_or_b32_e32 v42, 50, v64
	global_store_short v[16:17], v0, off offset:64
	v_mul_f32_e32 v0, 0x3b000000, v2
	v_ashrrev_i32_e32 v43, 31, v42
	v_cvt_pk_bf16_f32 v0, v0, v0
	v_mul_f32_e32 v26, 0x3b000000, v26
	v_lshlrev_b64 v[42:43], 11, v[42:43]
	global_store_short v[34:35], v0, off offset:64
	v_mul_f32_e32 v0, 0x3b000000, v3
	v_cvt_pk_bf16_f32 v26, v26, v26
	v_lshl_add_u64 v[42:43], v[66:67], 0, v[42:43]
	v_cvt_pk_bf16_f32 v0, v0, v0
	global_store_short v[42:43], v26, off
	v_mul_f32_e32 v26, 0x3b000000, v27
	global_store_short v[18:19], v0, off offset:64
	v_mul_f32_e32 v0, 0x3b000000, v4
	v_cvt_pk_bf16_f32 v44, v26, v26
	v_or_b32_e32 v26, 51, v64
	v_cvt_pk_bf16_f32 v0, v0, v0
	v_ashrrev_i32_e32 v27, 31, v26
	global_store_short v[36:37], v0, off offset:64
	v_mul_f32_e32 v0, 0x3b000000, v5
	v_lshlrev_b64 v[26:27], 11, v[26:27]
	v_cvt_pk_bf16_f32 v0, v0, v0
	v_lshl_add_u64 v[26:27], v[66:67], 0, v[26:27]
	global_store_short v[20:21], v0, off offset:64
	v_mul_f32_e32 v0, 0x3b000000, v6
	global_store_short v[26:27], v44, off
	v_or_b32_e32 v44, 56, v64
	v_cvt_pk_bf16_f32 v0, v0, v0
	v_ashrrev_i32_e32 v45, 31, v44
	global_store_short v[38:39], v0, off offset:64
	v_mul_f32_e32 v0, 0x3b000000, v7
	v_mul_f32_e32 v28, 0x3b000000, v28
	v_lshlrev_b64 v[44:45], 11, v[44:45]
	v_cvt_pk_bf16_f32 v0, v0, v0
	v_cvt_pk_bf16_f32 v28, v28, v28
	v_lshl_add_u64 v[44:45], v[66:67], 0, v[44:45]
	global_store_short v[22:23], v0, off offset:64
	v_mul_f32_e32 v0, 0x3b000000, v8
	global_store_short v[44:45], v28, off
	v_mul_f32_e32 v28, 0x3b000000, v29
	v_cvt_pk_bf16_f32 v0, v0, v0
	v_cvt_pk_bf16_f32 v46, v28, v28
	v_or_b32_e32 v28, 57, v64
	global_store_short v[40:41], v0, off offset:64
	v_mul_f32_e32 v0, 0x3b000000, v9
	v_ashrrev_i32_e32 v29, 31, v28
	v_cvt_pk_bf16_f32 v0, v0, v0
	v_lshlrev_b64 v[28:29], 11, v[28:29]
	global_store_short v[24:25], v0, off offset:64
	v_mul_f32_e32 v0, 0x3b000000, v10
	v_lshl_add_u64 v[28:29], v[66:67], 0, v[28:29]
	v_cvt_pk_bf16_f32 v0, v0, v0
	global_store_short v[28:29], v46, off
	v_or_b32_e32 v46, 58, v64
	global_store_short v[42:43], v0, off offset:64
	v_mul_f32_e32 v0, 0x3b000000, v11
	v_ashrrev_i32_e32 v47, 31, v46
	v_cvt_pk_bf16_f32 v0, v0, v0
	v_mul_f32_e32 v30, 0x3b000000, v30
	v_lshlrev_b64 v[46:47], 11, v[46:47]
	global_store_short v[26:27], v0, off offset:64
	v_mul_f32_e32 v0, 0x3b000000, v12
	v_cvt_pk_bf16_f32 v30, v30, v30
	v_lshl_add_u64 v[46:47], v[66:67], 0, v[46:47]
	v_cvt_pk_bf16_f32 v0, v0, v0
	global_store_short v[46:47], v30, off
	v_mul_f32_e32 v30, 0x3b000000, v31
	global_store_short v[44:45], v0, off offset:64
	v_mul_f32_e32 v0, 0x3b000000, v13
	v_cvt_pk_bf16_f32 v48, v30, v30
	v_or_b32_e32 v30, 59, v64
	v_cvt_pk_bf16_f32 v0, v0, v0
	v_ashrrev_i32_e32 v31, 31, v30
	global_store_short v[28:29], v0, off offset:64
	v_mul_f32_e32 v0, 0x3b000000, v14
	v_lshlrev_b64 v[30:31], 11, v[30:31]
	v_cvt_pk_bf16_f32 v0, v0, v0
	v_lshl_add_u64 v[30:31], v[66:67], 0, v[30:31]
	global_store_short v[46:47], v0, off offset:64
	v_mul_f32_e32 v0, 0x3b000000, v15
	global_store_short v[62:63], v65, off
	global_store_short v[30:31], v48, off
	v_cvt_pk_bf16_f32 v0, v0, v0
	global_store_short v[30:31], v0, off offset:64
